# gs-load hoist in weight conversion + P1 sample tiles moved to 1-unit workgroups with pipelined loads + rot=0
# speedup vs baseline: 1.0000x; 1.0000x over previous
; #define LAS __attribute__((address_space(3)))
; __device__ __forceinline__ void p0_t_finish(const TItem& t, int lane, const f32x4 (&v)[8], LAS float* scr) {
; #pragma unroll
;     for (int i = 0; i < 8; ++i) { const int kk = 8 * i + (lane >> 3); f32x4 x = v[i]; if (t.gs) x = x * t.gs[t.k0 + kk]; LAS float* d = scr + kk * 33 + 4 * (lane & 7); d[0] = x[0]; d[1] = x[1]; d[2] = x[2]; d[3] = x[3]; }
.LBB0_21:
	s_lshl_b32 s24, s15, 10
	s_ashr_i32 s25, s24, 31
	s_lshl_b64 s[24:25], s[24:25], 2
	s_add_u32 s24, s2, s24
	s_addc_u32 s25, s3, s25
	s_cmp_lg_u64 s[2:3], 0
	s_cselect_b64 s[26:27], -1, 0
	s_cmp_eq_u64 s[2:3], 0
	s_mov_b64 s[2:3], -1
	s_cbranch_scc1 .LBB0_23
	s_ashr_i32 s23, s22, 31
	v_ashrrev_i32_e32 v79, 31, v78
	v_lshl_add_u64 v[68:69], s[22:23], 0, v[70:71]
	v_lshl_add_u64 v[66:67], v[78:79], 2, s[24:25]
	v_lshl_add_u64 v[68:69], v[68:69], 2, s[24:25]
	global_load_dword v66, v[66:67], off
	s_mov_b64 s[2:3], 0
	global_load_dword v108, v[68:69], off offset:64
	global_load_dword v109, v[68:69], off offset:96
	global_load_dword v110, v[68:69], off offset:128
	global_load_dword v111, v[68:69], off offset:160
	global_load_dword v112, v[68:69], off offset:192
	global_load_dword v113, v[68:69], off offset:224
	global_load_dword v92, v[68:69], off offset:32
	s_waitcnt vmcnt(1)
	v_pk_mul_f32 v[78:79], v[60:61], v[66:67] op_sel_hi:[1,0]
	v_pk_mul_f32 v[80:81], v[58:59], v[66:67] op_sel_hi:[1,0]
	s_waitcnt vmcnt(0)
	v_pk_mul_f32 v[68:69], v[64:65], v[92:93] op_sel_hi:[1,0]
	v_pk_mul_f32 v[66:67], v[62:63], v[92:93] op_sel_hi:[1,0]

; #define LAS __attribute__((address_space(3)))
; __device__ __forceinline__ void p0_t_finish(const TItem& t, int lane, const f32x4 (&v)[8], LAS float* scr) {
; #pragma unroll
;     for (int i = 0; i < 8; ++i) { const int kk = 8 * i + (lane >> 3); f32x4 x = v[i]; if (t.gs) x = x * t.gs[t.k0 + kk]; LAS float* d = scr + kk * 33 + 4 * (lane & 7); d[0] = x[0]; d[1] = x[1]; d[2] = x[2]; d[3] = x[3]; }
.LBB0_25:
	v_add_u32_e32 v75, 0x420, v90
	s_waitcnt vmcnt(7)
	v_cndmask_b32_e64 v58, 0, 1, s[26:27]
	ds_write2_b32 v90, v80, v81 offset1:1
	ds_write2_b32 v90, v78, v79 offset0:2 offset1:3
	ds_write2_b32 v75, v66, v67 offset1:1
	v_add_u32_e32 v66, 0x428, v90
	v_cmp_ne_u32_e64 s[2:3], 1, v58
	s_andn2_b64 vcc, exec, s[26:27]
	s_mov_b64 s[26:27], -1
	ds_write2_b32 v66, v68, v69 offset1:1
	s_cbranch_vccnz .LBB0_27
	s_ashr_i32 s23, s22, 31
	v_lshl_add_u64 v[58:59], s[22:23], 0, v[70:71]
	v_lshl_add_u64 v[58:59], v[58:59], 2, s[24:25]
	v_mov_b32_e32 v60, v108
	s_nop 0
	v_mov_b32_e32 v58, v109
	s_mov_b64 s[26:27], 0
	s_waitcnt vmcnt(1)
	v_pk_mul_f32 v[62:63], v[52:53], v[60:61] op_sel_hi:[1,0]
	v_pk_mul_f32 v[64:65], v[50:51], v[60:61] op_sel_hi:[1,0]
	s_waitcnt vmcnt(0)
	v_pk_mul_f32 v[60:61], v[56:57], v[58:59] op_sel_hi:[1,0]
	v_pk_mul_f32 v[58:59], v[54:55], v[58:59] op_sel_hi:[1,0]

; #define LAS __attribute__((address_space(3)))
; __device__ __forceinline__ void p0_t_finish(const TItem& t, int lane, const f32x4 (&v)[8], LAS float* scr) {
; #pragma unroll
;     for (int i = 0; i < 8; ++i) { const int kk = 8 * i + (lane >> 3); f32x4 x = v[i]; if (t.gs) x = x * t.gs[t.k0 + kk]; LAS float* d = scr + kk * 33 + 4 * (lane & 7); d[0] = x[0]; d[1] = x[1]; d[2] = x[2]; d[3] = x[3]; }
.LBB0_29:
	v_add_u32_e32 v67, 0x840, v90
	s_waitcnt vmcnt(6)
	ds_write2_b32 v67, v64, v65 offset1:1
	v_add_u32_e32 v64, 0x848, v90
	ds_write2_b32 v64, v62, v63 offset1:1
	v_add_u32_e32 v62, 0xc60, v90
	ds_write2_b32 v62, v58, v59 offset1:1
	v_add_u32_e32 v58, 0xc68, v90
	s_and_b64 vcc, exec, s[2:3]
	s_mov_b64 s[26:27], -1
	ds_write2_b32 v58, v60, v61 offset1:1
	s_cbranch_vccnz .LBB0_31
	s_ashr_i32 s23, s22, 31
	s_waitcnt vmcnt(5)
	v_lshl_add_u64 v[50:51], s[22:23], 0, v[70:71]
	v_lshl_add_u64 v[50:51], v[50:51], 2, s[24:25]
	v_mov_b32_e32 v52, v110
	s_nop 0
	v_mov_b32_e32 v50, v111
	s_mov_b64 s[26:27], 0
	s_waitcnt vmcnt(1)
	v_pk_mul_f32 v[54:55], v[44:45], v[52:53] op_sel_hi:[1,0]
	v_pk_mul_f32 v[56:57], v[42:43], v[52:53] op_sel_hi:[1,0]
	s_waitcnt vmcnt(0)
	v_pk_mul_f32 v[52:53], v[48:49], v[50:51] op_sel_hi:[1,0]
	v_pk_mul_f32 v[50:51], v[46:47], v[50:51] op_sel_hi:[1,0]

; #define LAS __attribute__((address_space(3)))
; __device__ __forceinline__ void p0_t_finish(const TItem& t, int lane, const f32x4 (&v)[8], LAS float* scr) {
; #pragma unroll
;     for (int i = 0; i < 8; ++i) { const int kk = 8 * i + (lane >> 3); f32x4 x = v[i]; if (t.gs) x = x * t.gs[t.k0 + kk]; LAS float* d = scr + kk * 33 + 4 * (lane & 7); d[0] = x[0]; d[1] = x[1]; d[2] = x[2]; d[3] = x[3]; }
.LBB0_33:
	v_add_u32_e32 v59, 0x1080, v90
	s_waitcnt vmcnt(4)
	ds_write2_b32 v59, v56, v57 offset1:1
	v_add_u32_e32 v56, 0x1088, v90
	ds_write2_b32 v56, v54, v55 offset1:1
	v_add_u32_e32 v54, 0x14a0, v90
	ds_write2_b32 v54, v50, v51 offset1:1
	v_add_u32_e32 v50, 0x14a8, v90
	s_and_b64 vcc, exec, s[2:3]
	s_mov_b64 s[2:3], -1
	ds_write2_b32 v50, v52, v53 offset1:1
	s_cbranch_vccnz .LBB0_35
	s_ashr_i32 s23, s22, 31
	s_waitcnt vmcnt(3)
	v_lshl_add_u64 v[42:43], s[22:23], 0, v[70:71]
	v_lshl_add_u64 v[42:43], v[42:43], 2, s[24:25]
	v_mov_b32_e32 v44, v112
	s_nop 0
	v_mov_b32_e32 v42, v113
	s_mov_b64 s[2:3], 0
	s_waitcnt vmcnt(1)
	v_pk_mul_f32 v[46:47], v[36:37], v[44:45] op_sel_hi:[1,0]
	v_pk_mul_f32 v[48:49], v[34:35], v[44:45] op_sel_hi:[1,0]
	s_waitcnt vmcnt(0)
	v_pk_mul_f32 v[44:45], v[40:41], v[42:43] op_sel_hi:[1,0]
	v_pk_mul_f32 v[42:43], v[38:39], v[42:43] op_sel_hi:[1,0]

; #define GAS __attribute__((address_space(1)))
; #define LAS __attribute__((address_space(3)))
; #define LDS_WAIT() asm volatile("s_waitcnt lgkmcnt(0)" ::: "memory")
; __device__ __forceinline__ unsigned pk2(float lo, float hi) { unsigned r; asm("v_cvt_pk_bf16_f32 %0, %1, %2" : "=v"(r) : "v"(lo), "v"(hi)); return r; }
; __device__ __forceinline__ void p0_t_finish(const TItem& t, int lane, const f32x4 (&v)[8], LAS float* scr) {
; #pragma unroll
;     for (int i = 0; i < 8; ++i) { const int kk = 8 * i + (lane >> 3); f32x4 x = v[i]; if (t.gs) x = x * t.gs[t.k0 + kk]; LAS float* d = scr + kk * 33 + 4 * (lane & 7); d[0] = x[0]; d[1] = x[1]; d[2] = x[2]; d[3] = x[3]; }
;     LDS_WAIT(); asm volatile("" ::: "memory");
;     const int c = lane & 7;
; #pragma unroll
;     for (int j = 0; j < 4; ++j) { const int n = (lane >> 3) + 8 * j; const LAS float* s = scr + (8 * c) * 33 + n;
;         v4u o; o.x = pk2(s[0 * 33], s[1 * 33]); o.y = pk2(s[2 * 33], s[3 * 33]); o.z = pk2(s[4 * 33], s[5 * 33]); o.w = pk2(s[6 * 33], s[7 * 33]);
;         *(GAS v4u*)(t.WT + (size_t)(t.n0 + n) * t.K + t.k0 + 8 * c) = o; }
.LBB0_37:
	v_add_u32_e32 v51, 0x18c0, v90
	s_waitcnt vmcnt(2)
	ds_write2_b32 v51, v48, v49 offset1:1
	v_add_u32_e32 v48, 0x18c8, v90
	ds_write2_b32 v48, v46, v47 offset1:1
	v_add_u32_e32 v46, 0x1ce0, v90
	ds_write2_b32 v46, v42, v43 offset1:1
	v_add_u32_e32 v42, 0x1ce8, v90
	ds_write2_b32 v42, v44, v45 offset1:1
	s_waitcnt lgkmcnt(0)
	s_mul_hi_i32 s3, s15, 0x1800000
	s_mul_i32 s15, s15, 0x1800000
	v_or_b32_e32 v92, s20, v70
	s_add_u32 s2, s9, s15
	s_waitcnt vmcnt(0)
	ds_read2_b32 v[38:39], v89 offset0:33 offset1:41
	ds_read2_b32 v[40:41], v89 offset1:8
	ds_read2_b32 v[44:45], v89 offset0:66 offset1:74
	ds_read2_b32 v[52:53], v89 offset0:99 offset1:107
	ds_read2_b32 v[60:61], v89 offset0:132 offset1:140
	ds_read2_b32 v[68:69], v89 offset0:165 offset1:173
	ds_read2_b32 v[78:79], v89 offset0:198 offset1:206
	ds_read2_b32 v[80:81], v89 offset0:231 offset1:239
	v_ashrrev_i32_e32 v93, 31, v92
	s_addc_u32 s3, s11, s3
	v_lshlrev_b64 v[92:93], 11, v[92:93]
	v_lshl_add_u64 v[92:93], s[2:3], 0, v[92:93]
	s_lshl_b64 s[22:23], s[22:23], 1
	v_lshl_add_u64 v[92:93], v[92:93], 0, s[22:23]
	s_waitcnt lgkmcnt(6)
	v_cvt_pk_bf16_f32 v34, v40, v38
	v_lshl_add_u64 v[92:93], v[92:93], 0, v[72:73]
	v_or_b32_e32 v38, s20, v82
	s_waitcnt lgkmcnt(4)
	v_cvt_pk_bf16_f32 v35, v44, v52
	s_waitcnt lgkmcnt(2)
	v_cvt_pk_bf16_f32 v36, v60, v68
	s_waitcnt lgkmcnt(0)
	v_cvt_pk_bf16_f32 v37, v78, v80
	global_store_dwordx4 v[92:93], v[34:37], off
	s_andn2_b64 vcc, exec, s[18:19]
	s_nop 0
	v_cvt_pk_bf16_f32 v34, v41, v39
	v_ashrrev_i32_e32 v39, 31, v38
	v_lshlrev_b64 v[38:39], 11, v[38:39]
	v_lshl_add_u64 v[38:39], s[2:3], 0, v[38:39]
	v_lshl_add_u64 v[38:39], v[38:39], 0, s[22:23]
	v_lshl_add_u64 v[38:39], v[38:39], 0, v[72:73]
	v_cvt_pk_bf16_f32 v35, v45, v53
	v_cvt_pk_bf16_f32 v36, v61, v69
	v_cvt_pk_bf16_f32 v37, v79, v81
	ds_read2_b32 v[40:41], v89 offset0:16 offset1:24
	ds_read2_b32 v[44:45], v89 offset0:49 offset1:57
	ds_read2_b32 v[52:53], v89 offset0:82 offset1:90
	ds_read2_b32 v[60:61], v89 offset0:115 offset1:123
	ds_read2_b32 v[68:69], v89 offset0:148 offset1:156
	ds_read2_b32 v[78:79], v89 offset0:181 offset1:189
	ds_read2_b32 v[80:81], v89 offset0:214 offset1:222
	ds_read2_b32 v[92:93], v89 offset0:247 offset1:255
	global_store_dwordx4 v[38:39], v[34:37], off
	v_or_b32_e32 v38, s20, v83
	v_ashrrev_i32_e32 v39, 31, v38
	v_lshlrev_b64 v[38:39], 11, v[38:39]
	v_lshl_add_u64 v[38:39], s[2:3], 0, v[38:39]
	v_lshl_add_u64 v[38:39], v[38:39], 0, s[22:23]
	v_lshl_add_u64 v[38:39], v[38:39], 0, v[72:73]
	s_waitcnt lgkmcnt(6)
	v_cvt_pk_bf16_f32 v34, v40, v44
	s_waitcnt lgkmcnt(4)
	v_cvt_pk_bf16_f32 v35, v52, v60
	s_waitcnt lgkmcnt(2)
	v_cvt_pk_bf16_f32 v36, v68, v78
	s_waitcnt lgkmcnt(0)
	v_cvt_pk_bf16_f32 v37, v80, v92
	global_store_dwordx4 v[38:39], v[34:37], off
	v_or_b32_e32 v38, s20, v84
	v_ashrrev_i32_e32 v39, 31, v38
	v_lshlrev_b64 v[38:39], 11, v[38:39]
	v_lshl_add_u64 v[38:39], s[2:3], 0, v[38:39]
	v_lshl_add_u64 v[38:39], v[38:39], 0, s[22:23]
	v_lshl_add_u64 v[38:39], v[38:39], 0, v[72:73]
	v_cvt_pk_bf16_f32 v34, v41, v45
	v_cvt_pk_bf16_f32 v35, v53, v61
	v_cvt_pk_bf16_f32 v36, v69, v79
	v_cvt_pk_bf16_f32 v37, v81, v93
	global_store_dwordx4 v[38:39], v[34:37], off
	s_waitcnt lgkmcnt(0)
	s_cbranch_vccnz .LBB0_18
	s_cmp_lg_u64 s[6:7], 0
	s_cselect_b64 s[18:19], -1, 0
	s_cmp_eq_u64 s[6:7], 0
	s_cbranch_scc1 .LBB0_49
	v_add_u32_e32 v34, s14, v70
	v_ashrrev_i32_e32 v35, 31, v34
	v_lshl_add_u64 v[34:35], v[34:35], 2, s[6:7]
	global_load_dword v36, v[34:35], off
	s_nop 0
	global_load_dword v114, v[34:35], off offset:64
	global_load_dword v115, v[34:35], off offset:96
	global_load_dword v116, v[34:35], off offset:128
	global_load_dword v117, v[34:35], off offset:160
	global_load_dword v118, v[34:35], off offset:192
	global_load_dword v119, v[34:35], off offset:224
	global_load_dword v34, v[34:35], off offset:32
	s_waitcnt vmcnt(1)
	v_pk_mul_f32 v[38:39], v[4:5], v[36:37] op_sel_hi:[1,0]
	v_pk_mul_f32 v[40:41], v[2:3], v[36:37] op_sel_hi:[1,0]
	s_waitcnt vmcnt(0)
	v_pk_mul_f32 v[36:37], v[8:9], v[34:35] op_sel_hi:[1,0]
	v_pk_mul_f32 v[34:35], v[6:7], v[34:35] op_sel_hi:[1,0]
	s_cbranch_execnz .LBB0_41

; #define LAS __attribute__((address_space(3)))
; __device__ __forceinline__ void p0_t_finish(const TItem& t, int lane, const f32x4 (&v)[8], LAS float* scr) {
; #pragma unroll
;     for (int i = 0; i < 8; ++i) { const int kk = 8 * i + (lane >> 3); f32x4 x = v[i]; if (t.gs) x = x * t.gs[t.k0 + kk]; LAS float* d = scr + kk * 33 + 4 * (lane & 7); d[0] = x[0]; d[1] = x[1]; d[2] = x[2]; d[3] = x[3]; }
.LBB0_41:
	ds_write2_b32 v90, v40, v41 offset1:1
	ds_write2_b32 v90, v38, v39 offset0:2 offset1:3
	ds_write2_b32 v75, v34, v35 offset1:1
	v_cndmask_b32_e64 v34, 0, 1, s[18:19]
	v_cmp_ne_u32_e64 s[2:3], 1, v34
	s_andn2_b64 vcc, exec, s[18:19]
	ds_write2_b32 v66, v36, v37 offset1:1
	s_cbranch_vccnz .LBB0_50
	s_ashr_i32 s15, s14, 31
	v_lshl_add_u64 v[34:35], s[14:15], 0, v[70:71]
	v_lshl_add_u64 v[34:35], v[34:35], 2, s[6:7]
	v_mov_b32_e32 v36, v114
	s_nop 0
	v_mov_b32_e32 v34, v115
	s_waitcnt vmcnt(1)
	v_pk_mul_f32 v[38:39], v[12:13], v[36:37] op_sel_hi:[1,0]
	v_pk_mul_f32 v[40:41], v[10:11], v[36:37] op_sel_hi:[1,0]
	s_waitcnt vmcnt(0)
	v_pk_mul_f32 v[36:37], v[16:17], v[34:35] op_sel_hi:[1,0]
	v_pk_mul_f32 v[34:35], v[14:15], v[34:35] op_sel_hi:[1,0]
	s_cbranch_execnz .LBB0_44

; #define LAS __attribute__((address_space(3)))
; __device__ __forceinline__ void p0_t_finish(const TItem& t, int lane, const f32x4 (&v)[8], LAS float* scr) {
; #pragma unroll
;     for (int i = 0; i < 8; ++i) { const int kk = 8 * i + (lane >> 3); f32x4 x = v[i]; if (t.gs) x = x * t.gs[t.k0 + kk]; LAS float* d = scr + kk * 33 + 4 * (lane & 7); d[0] = x[0]; d[1] = x[1]; d[2] = x[2]; d[3] = x[3]; }
.LBB0_44:
	s_and_b64 vcc, exec, s[2:3]
	ds_write2_b32 v67, v40, v41 offset1:1
	ds_write2_b32 v64, v38, v39 offset1:1
	ds_write2_b32 v62, v34, v35 offset1:1
	ds_write2_b32 v58, v36, v37 offset1:1
	s_cbranch_vccnz .LBB0_51
	s_ashr_i32 s15, s14, 31
	v_lshl_add_u64 v[34:35], s[14:15], 0, v[70:71]
	v_lshl_add_u64 v[34:35], v[34:35], 2, s[6:7]
	v_mov_b32_e32 v36, v116
	s_nop 0
	v_mov_b32_e32 v34, v117
	s_waitcnt vmcnt(1)
	v_pk_mul_f32 v[38:39], v[20:21], v[36:37] op_sel_hi:[1,0]
	v_pk_mul_f32 v[40:41], v[18:19], v[36:37] op_sel_hi:[1,0]
	s_waitcnt vmcnt(0)
	v_pk_mul_f32 v[36:37], v[24:25], v[34:35] op_sel_hi:[1,0]
	v_pk_mul_f32 v[34:35], v[22:23], v[34:35] op_sel_hi:[1,0]
	s_cbranch_execnz .LBB0_47

; #define LAS __attribute__((address_space(3)))
; __device__ __forceinline__ void p0_t_finish(const TItem& t, int lane, const f32x4 (&v)[8], LAS float* scr) {
; #pragma unroll
;     for (int i = 0; i < 8; ++i) { const int kk = 8 * i + (lane >> 3); f32x4 x = v[i]; if (t.gs) x = x * t.gs[t.k0 + kk]; LAS float* d = scr + kk * 33 + 4 * (lane & 7); d[0] = x[0]; d[1] = x[1]; d[2] = x[2]; d[3] = x[3]; }
.LBB0_47:
	s_and_b64 vcc, exec, s[2:3]
	ds_write2_b32 v59, v40, v41 offset1:1
	ds_write2_b32 v56, v38, v39 offset1:1
	ds_write2_b32 v54, v34, v35 offset1:1
	ds_write2_b32 v50, v36, v37 offset1:1
	s_cbranch_vccnz .LBB0_52
	s_ashr_i32 s15, s14, 31
	v_lshl_add_u64 v[34:35], s[14:15], 0, v[70:71]
	v_lshl_add_u64 v[34:35], v[34:35], 2, s[6:7]
	v_mov_b32_e32 v36, v118
	s_nop 0
	v_mov_b32_e32 v34, v119
	s_waitcnt vmcnt(1)
	v_pk_mul_f32 v[38:39], v[28:29], v[36:37] op_sel_hi:[1,0]
	v_pk_mul_f32 v[40:41], v[26:27], v[36:37] op_sel_hi:[1,0]
	s_waitcnt vmcnt(0)
	v_pk_mul_f32 v[36:37], v[32:33], v[34:35] op_sel_hi:[1,0]
	v_pk_mul_f32 v[34:35], v[30:31], v[34:35] op_sel_hi:[1,0]
	s_cbranch_execnz .LBB0_17
	s_branch .LBB0_53

; #define LAS __attribute__((address_space(3)))
; __device__ __forceinline__ void p0_t_finish(const TItem& t, int lane, const f32x4 (&v)[8], LAS float* scr) {
; #pragma unroll
;     for (int i = 0; i < 8; ++i) { const int kk = 8 * i + (lane >> 3); f32x4 x = v[i]; if (t.gs) x = x * t.gs[t.k0 + kk]; LAS float* d = scr + kk * 33 + 4 * (lane & 7); d[0] = x[0]; d[1] = x[1]; d[2] = x[2]; d[3] = x[3]; }
.LBB0_247:
	s_cmp_lg_u64 s[30:31], 0
	s_cselect_b64 s[46:47], -1, 0
	s_cmp_eq_u64 s[30:31], 0
	s_cbranch_scc1 .LBB0_271
	s_ashr_i32 s45, s44, 31
	v_ashrrev_i32_e32 v69, 31, v68
	v_lshl_add_u64 v[70:71], s[44:45], 0, v[72:73]
	v_lshl_add_u64 v[68:69], v[68:69], 2, s[30:31]
	v_lshl_add_u64 v[70:71], v[70:71], 2, s[30:31]
	global_load_dword v68, v[68:69], off
	s_nop 0
	global_load_dword v108, v[70:71], off offset:64
	global_load_dword v109, v[70:71], off offset:96
	global_load_dword v110, v[70:71], off offset:128
	global_load_dword v111, v[70:71], off offset:160
	global_load_dword v112, v[70:71], off offset:192
	global_load_dword v113, v[70:71], off offset:224
	global_load_dword v90, v[70:71], off offset:32
	s_waitcnt vmcnt(0)
	v_pk_mul_f32 v[76:77], v[62:63], v[68:69] op_sel_hi:[1,0]
	v_pk_mul_f32 v[78:79], v[60:61], v[68:69] op_sel_hi:[1,0]
	s_waitcnt vmcnt(0)
	v_pk_mul_f32 v[70:71], v[66:67], v[90:91] op_sel_hi:[1,0]
	v_pk_mul_f32 v[68:69], v[64:65], v[90:91] op_sel_hi:[1,0]
	s_cbranch_execnz .LBB0_250

; #define LAS __attribute__((address_space(3)))
; __device__ __forceinline__ void p0_t_finish(const TItem& t, int lane, const f32x4 (&v)[8], LAS float* scr) {
; #pragma unroll
;     for (int i = 0; i < 8; ++i) { const int kk = 8 * i + (lane >> 3); f32x4 x = v[i]; if (t.gs) x = x * t.gs[t.k0 + kk]; LAS float* d = scr + kk * 33 + 4 * (lane & 7); d[0] = x[0]; d[1] = x[1]; d[2] = x[2]; d[3] = x[3]; }
.LBB0_250:
	ds_write2_b32 v88, v78, v79 offset1:1
	ds_write2_b32 v88, v76, v77 offset0:2 offset1:3
	v_add_u32_e32 v76, 0x420, v88
	s_waitcnt vmcnt(0)
	v_cndmask_b32_e64 v60, 0, 1, s[46:47]
	ds_write2_b32 v76, v68, v69 offset1:1
	v_add_u32_e32 v68, 0x428, v88
	v_cmp_ne_u32_e64 s[0:1], 1, v60
	s_andn2_b64 vcc, exec, s[46:47]
	ds_write2_b32 v68, v70, v71 offset1:1
	s_cbranch_vccnz .LBB0_272
	s_ashr_i32 s45, s44, 31
	v_lshl_add_u64 v[60:61], s[44:45], 0, v[72:73]
	v_lshl_add_u64 v[60:61], v[60:61], 2, s[30:31]
	v_mov_b32_e32 v62, v108
	s_nop 0
	v_mov_b32_e32 v60, v109
	s_waitcnt vmcnt(0)
	v_pk_mul_f32 v[64:65], v[54:55], v[62:63] op_sel_hi:[1,0]
	v_pk_mul_f32 v[66:67], v[52:53], v[62:63] op_sel_hi:[1,0]
	s_waitcnt vmcnt(0)
	v_pk_mul_f32 v[62:63], v[58:59], v[60:61] op_sel_hi:[1,0]
	v_pk_mul_f32 v[60:61], v[56:57], v[60:61] op_sel_hi:[1,0]
	s_cbranch_execnz .LBB0_253

; #define LAS __attribute__((address_space(3)))
; __device__ __forceinline__ void p0_t_finish(const TItem& t, int lane, const f32x4 (&v)[8], LAS float* scr) {
; #pragma unroll
;     for (int i = 0; i < 8; ++i) { const int kk = 8 * i + (lane >> 3); f32x4 x = v[i]; if (t.gs) x = x * t.gs[t.k0 + kk]; LAS float* d = scr + kk * 33 + 4 * (lane & 7); d[0] = x[0]; d[1] = x[1]; d[2] = x[2]; d[3] = x[3]; }
.LBB0_253:
	v_add_u32_e32 v69, 0x840, v88
	s_waitcnt vmcnt(0)
	ds_write2_b32 v69, v66, v67 offset1:1
	v_add_u32_e32 v66, 0x848, v88
	ds_write2_b32 v66, v64, v65 offset1:1
	v_add_u32_e32 v64, 0xc60, v88
	ds_write2_b32 v64, v60, v61 offset1:1
	v_add_u32_e32 v60, 0xc68, v88
	s_and_b64 vcc, exec, s[0:1]
	ds_write2_b32 v60, v62, v63 offset1:1
	s_cbranch_vccnz .LBB0_273
	s_ashr_i32 s45, s44, 31
	s_waitcnt vmcnt(0)
	v_lshl_add_u64 v[52:53], s[44:45], 0, v[72:73]
	v_lshl_add_u64 v[52:53], v[52:53], 2, s[30:31]
	v_mov_b32_e32 v54, v110
	s_nop 0
	v_mov_b32_e32 v52, v111
	s_waitcnt vmcnt(0)
	v_pk_mul_f32 v[56:57], v[46:47], v[54:55] op_sel_hi:[1,0]
	v_pk_mul_f32 v[58:59], v[44:45], v[54:55] op_sel_hi:[1,0]
	s_waitcnt vmcnt(0)
	v_pk_mul_f32 v[54:55], v[50:51], v[52:53] op_sel_hi:[1,0]
	v_pk_mul_f32 v[52:53], v[48:49], v[52:53] op_sel_hi:[1,0]
	s_cbranch_execnz .LBB0_256

; #define LAS __attribute__((address_space(3)))
; __device__ __forceinline__ void p0_t_finish(const TItem& t, int lane, const f32x4 (&v)[8], LAS float* scr) {
; #pragma unroll
;     for (int i = 0; i < 8; ++i) { const int kk = 8 * i + (lane >> 3); f32x4 x = v[i]; if (t.gs) x = x * t.gs[t.k0 + kk]; LAS float* d = scr + kk * 33 + 4 * (lane & 7); d[0] = x[0]; d[1] = x[1]; d[2] = x[2]; d[3] = x[3]; }
.LBB0_256:
	v_add_u32_e32 v61, 0x1080, v88
	s_waitcnt vmcnt(0)
	ds_write2_b32 v61, v58, v59 offset1:1
	v_add_u32_e32 v58, 0x1088, v88
	ds_write2_b32 v58, v56, v57 offset1:1
	v_add_u32_e32 v56, 0x14a0, v88
	ds_write2_b32 v56, v52, v53 offset1:1
	v_add_u32_e32 v52, 0x14a8, v88
	s_and_b64 vcc, exec, s[0:1]
	ds_write2_b32 v52, v54, v55 offset1:1
	s_cbranch_vccnz .LBB0_274
	s_ashr_i32 s45, s44, 31
	s_waitcnt vmcnt(0)
	v_lshl_add_u64 v[44:45], s[44:45], 0, v[72:73]
	v_lshl_add_u64 v[44:45], v[44:45], 2, s[30:31]
	v_mov_b32_e32 v46, v112
	s_nop 0
	v_mov_b32_e32 v44, v113
	s_waitcnt vmcnt(0)
	v_pk_mul_f32 v[48:49], v[38:39], v[46:47] op_sel_hi:[1,0]
	v_pk_mul_f32 v[50:51], v[36:37], v[46:47] op_sel_hi:[1,0]
	s_waitcnt vmcnt(0)
	v_pk_mul_f32 v[46:47], v[42:43], v[44:45] op_sel_hi:[1,0]
	v_pk_mul_f32 v[44:45], v[40:41], v[44:45] op_sel_hi:[1,0]
	s_cbranch_execnz .LBB0_259

; #define GAS __attribute__((address_space(1)))
; #define LAS __attribute__((address_space(3)))
; #define LDS_WAIT() asm volatile("s_waitcnt lgkmcnt(0)" ::: "memory")
; __device__ __forceinline__ unsigned pk2(float lo, float hi) { unsigned r; asm("v_cvt_pk_bf16_f32 %0, %1, %2" : "=v"(r) : "v"(lo), "v"(hi)); return r; }
; __device__ __forceinline__ void p0_t_finish(const TItem& t, int lane, const f32x4 (&v)[8], LAS float* scr) {
; #pragma unroll
;     for (int i = 0; i < 8; ++i) { const int kk = 8 * i + (lane >> 3); f32x4 x = v[i]; if (t.gs) x = x * t.gs[t.k0 + kk]; LAS float* d = scr + kk * 33 + 4 * (lane & 7); d[0] = x[0]; d[1] = x[1]; d[2] = x[2]; d[3] = x[3]; }
;     LDS_WAIT(); asm volatile("" ::: "memory");
;     const int c = lane & 7;
; #pragma unroll
;     for (int j = 0; j < 4; ++j) { const int n = (lane >> 3) + 8 * j; const LAS float* s = scr + (8 * c) * 33 + n;
;         v4u o; o.x = pk2(s[0 * 33], s[1 * 33]); o.y = pk2(s[2 * 33], s[3 * 33]); o.z = pk2(s[4 * 33], s[5 * 33]); o.w = pk2(s[6 * 33], s[7 * 33]);
;         *(GAS v4u*)(t.WT + (size_t)(t.n0 + n) * t.K + t.k0 + 8 * c) = o; }
.LBB0_259:
	v_add_u32_e32 v53, 0x18c0, v88
	s_waitcnt vmcnt(0)
	ds_write2_b32 v53, v50, v51 offset1:1
	v_add_u32_e32 v50, 0x18c8, v88
	ds_write2_b32 v50, v48, v49 offset1:1
	v_add_u32_e32 v48, 0x1ce0, v88
	ds_write2_b32 v48, v44, v45 offset1:1
	v_add_u32_e32 v44, 0x1ce8, v88
	ds_write2_b32 v44, v46, v47 offset1:1
	s_waitcnt lgkmcnt(0)
	s_waitcnt vmcnt(0)
	ds_read2_b32 v[40:41], v87 offset0:33 offset1:41
	ds_read2_b32 v[42:43], v87 offset1:8
	ds_read2_b32 v[46:47], v87 offset0:66 offset1:74
	ds_read2_b32 v[54:55], v87 offset0:99 offset1:107
	ds_read2_b32 v[62:63], v87 offset0:132 offset1:140
	ds_read2_b32 v[70:71], v87 offset0:165 offset1:173
	ds_read2_b32 v[78:79], v87 offset0:198 offset1:206
	ds_read2_b32 v[90:91], v87 offset0:231 offset1:239
	s_waitcnt lgkmcnt(6)
	v_cvt_pk_bf16_f32 v36, v42, v40
	v_or_b32_e32 v40, s42, v72
	v_mul_hi_i32_i24_e32 v93, s26, v40
	v_mul_i32_i24_e32 v92, s26, v40
	v_lshl_add_u64 v[92:93], v[92:93], 1, s[24:25]
	s_lshl_b64 s[0:1], s[44:45], 1
	v_lshl_add_u64 v[92:93], v[92:93], 0, s[0:1]
	v_mov_b32_e32 v75, v3
	v_lshl_add_u64 v[92:93], v[92:93], 0, v[74:75]
	v_or_b32_e32 v40, s42, v80
	s_waitcnt lgkmcnt(4)
	v_cvt_pk_bf16_f32 v37, v46, v54
	s_waitcnt lgkmcnt(2)
	v_cvt_pk_bf16_f32 v38, v62, v70
	s_waitcnt lgkmcnt(0)
	v_cvt_pk_bf16_f32 v39, v78, v90
	global_store_dwordx4 v[92:93], v[36:39], off
	s_andn2_b64 vcc, exec, s[40:41]
	s_nop 0
	v_cvt_pk_bf16_f32 v36, v43, v41
	v_mul_hi_i32_i24_e32 v41, s26, v40
	v_mul_i32_i24_e32 v40, s26, v40
	v_lshl_add_u64 v[40:41], v[40:41], 1, s[24:25]
	v_lshl_add_u64 v[40:41], v[40:41], 0, s[0:1]
	v_lshl_add_u64 v[40:41], v[40:41], 0, v[74:75]
	v_cvt_pk_bf16_f32 v37, v47, v55
	v_cvt_pk_bf16_f32 v38, v63, v71
	v_cvt_pk_bf16_f32 v39, v79, v91
	ds_read2_b32 v[42:43], v87 offset0:16 offset1:24
	ds_read2_b32 v[46:47], v87 offset0:49 offset1:57
	ds_read2_b32 v[54:55], v87 offset0:82 offset1:90
	ds_read2_b32 v[62:63], v87 offset0:115 offset1:123
	ds_read2_b32 v[70:71], v87 offset0:148 offset1:156
	ds_read2_b32 v[78:79], v87 offset0:181 offset1:189
	ds_read2_b32 v[90:91], v87 offset0:214 offset1:222
	ds_read2_b32 v[92:93], v87 offset0:247 offset1:255
	global_store_dwordx4 v[40:41], v[36:39], off
	v_or_b32_e32 v40, s42, v81
	v_mul_hi_i32_i24_e32 v41, s26, v40
	v_mul_i32_i24_e32 v40, s26, v40
	v_lshl_add_u64 v[40:41], v[40:41], 1, s[24:25]
	v_lshl_add_u64 v[40:41], v[40:41], 0, s[0:1]
	v_lshl_add_u64 v[40:41], v[40:41], 0, v[74:75]
	s_waitcnt lgkmcnt(6)
	v_cvt_pk_bf16_f32 v36, v42, v46
	s_waitcnt lgkmcnt(4)
	v_cvt_pk_bf16_f32 v37, v54, v62
	s_waitcnt lgkmcnt(2)
	v_cvt_pk_bf16_f32 v38, v70, v78
	s_waitcnt lgkmcnt(0)
	v_cvt_pk_bf16_f32 v39, v90, v92
	global_store_dwordx4 v[40:41], v[36:39], off
	v_or_b32_e32 v40, s42, v82
	v_mul_hi_i32_i24_e32 v41, s26, v40
	v_mul_i32_i24_e32 v40, s26, v40
	v_lshl_add_u64 v[40:41], v[40:41], 1, s[24:25]
	v_lshl_add_u64 v[40:41], v[40:41], 0, s[0:1]
	v_lshl_add_u64 v[40:41], v[40:41], 0, v[74:75]
	v_cvt_pk_bf16_f32 v36, v43, v47
	v_cvt_pk_bf16_f32 v37, v55, v63
	v_cvt_pk_bf16_f32 v38, v71, v79
	v_cvt_pk_bf16_f32 v39, v91, v93
	global_store_dwordx4 v[40:41], v[36:39], off
	s_waitcnt lgkmcnt(0)
	s_cbranch_vccnz .LBB0_190
	s_cmp_lg_u64 s[18:19], 0
	s_cselect_b64 s[24:25], -1, 0
	s_cmp_eq_u64 s[18:19], 0
	s_cbranch_scc1 .LBB0_275
	v_add_u32_e32 v36, s20, v72
	v_ashrrev_i32_e32 v37, 31, v36
	v_lshl_add_u64 v[36:37], v[36:37], 2, s[18:19]
	global_load_dword v38, v[36:37], off
	s_nop 0
	global_load_dword v114, v[36:37], off offset:64
	global_load_dword v115, v[36:37], off offset:96
	global_load_dword v116, v[36:37], off offset:128
	global_load_dword v117, v[36:37], off offset:160
	global_load_dword v118, v[36:37], off offset:192
	global_load_dword v119, v[36:37], off offset:224
	global_load_dword v36, v[36:37], off offset:32
	s_waitcnt vmcnt(1)
	v_pk_mul_f32 v[40:41], v[6:7], v[38:39] op_sel_hi:[1,0]
	v_pk_mul_f32 v[42:43], v[4:5], v[38:39] op_sel_hi:[1,0]
	s_waitcnt vmcnt(0)
	v_pk_mul_f32 v[38:39], v[10:11], v[36:37] op_sel_hi:[1,0]
	v_pk_mul_f32 v[36:37], v[8:9], v[36:37] op_sel_hi:[1,0]
	s_cbranch_execnz .LBB0_263

; #define LAS __attribute__((address_space(3)))
; __device__ __forceinline__ void p0_t_finish(const TItem& t, int lane, const f32x4 (&v)[8], LAS float* scr) {
; #pragma unroll
;     for (int i = 0; i < 8; ++i) { const int kk = 8 * i + (lane >> 3); f32x4 x = v[i]; if (t.gs) x = x * t.gs[t.k0 + kk]; LAS float* d = scr + kk * 33 + 4 * (lane & 7); d[0] = x[0]; d[1] = x[1]; d[2] = x[2]; d[3] = x[3]; }
.LBB0_263:
	ds_write2_b32 v88, v42, v43 offset1:1
	ds_write2_b32 v88, v40, v41 offset0:2 offset1:3
	ds_write2_b32 v76, v36, v37 offset1:1
	v_cndmask_b32_e64 v36, 0, 1, s[24:25]
	v_cmp_ne_u32_e64 s[0:1], 1, v36
	s_andn2_b64 vcc, exec, s[24:25]
	ds_write2_b32 v68, v38, v39 offset1:1
	s_cbranch_vccnz .LBB0_276
	s_ashr_i32 s21, s20, 31
	v_lshl_add_u64 v[36:37], s[20:21], 0, v[72:73]
	v_lshl_add_u64 v[36:37], v[36:37], 2, s[18:19]
	v_mov_b32_e32 v38, v114
	s_nop 0
	v_mov_b32_e32 v36, v115
	s_waitcnt vmcnt(1)
	v_pk_mul_f32 v[40:41], v[14:15], v[38:39] op_sel_hi:[1,0]
	v_pk_mul_f32 v[42:43], v[12:13], v[38:39] op_sel_hi:[1,0]
	s_waitcnt vmcnt(0)
	v_pk_mul_f32 v[38:39], v[18:19], v[36:37] op_sel_hi:[1,0]
	v_pk_mul_f32 v[36:37], v[16:17], v[36:37] op_sel_hi:[1,0]
	s_cbranch_execnz .LBB0_266

; #define LAS __attribute__((address_space(3)))
; __device__ __forceinline__ void p0_t_finish(const TItem& t, int lane, const f32x4 (&v)[8], LAS float* scr) {
; #pragma unroll
;     for (int i = 0; i < 8; ++i) { const int kk = 8 * i + (lane >> 3); f32x4 x = v[i]; if (t.gs) x = x * t.gs[t.k0 + kk]; LAS float* d = scr + kk * 33 + 4 * (lane & 7); d[0] = x[0]; d[1] = x[1]; d[2] = x[2]; d[3] = x[3]; }
.LBB0_266:
	s_and_b64 vcc, exec, s[0:1]
	ds_write2_b32 v69, v42, v43 offset1:1
	ds_write2_b32 v66, v40, v41 offset1:1
	ds_write2_b32 v64, v36, v37 offset1:1
	ds_write2_b32 v60, v38, v39 offset1:1
	s_cbranch_vccnz .LBB0_277
	s_ashr_i32 s21, s20, 31
	v_lshl_add_u64 v[36:37], s[20:21], 0, v[72:73]
	v_lshl_add_u64 v[36:37], v[36:37], 2, s[18:19]
	v_mov_b32_e32 v38, v116
	s_nop 0
	v_mov_b32_e32 v36, v117
	s_waitcnt vmcnt(1)
	v_pk_mul_f32 v[40:41], v[22:23], v[38:39] op_sel_hi:[1,0]
	v_pk_mul_f32 v[42:43], v[20:21], v[38:39] op_sel_hi:[1,0]
	s_waitcnt vmcnt(0)
	v_pk_mul_f32 v[38:39], v[26:27], v[36:37] op_sel_hi:[1,0]
	v_pk_mul_f32 v[36:37], v[24:25], v[36:37] op_sel_hi:[1,0]
	s_cbranch_execnz .LBB0_269

; #define LAS __attribute__((address_space(3)))
; __device__ __forceinline__ void p0_t_finish(const TItem& t, int lane, const f32x4 (&v)[8], LAS float* scr) {
; #pragma unroll
;     for (int i = 0; i < 8; ++i) { const int kk = 8 * i + (lane >> 3); f32x4 x = v[i]; if (t.gs) x = x * t.gs[t.k0 + kk]; LAS float* d = scr + kk * 33 + 4 * (lane & 7); d[0] = x[0]; d[1] = x[1]; d[2] = x[2]; d[3] = x[3]; }
.LBB0_269:
	s_and_b64 vcc, exec, s[0:1]
	ds_write2_b32 v61, v42, v43 offset1:1
	ds_write2_b32 v58, v40, v41 offset1:1
	ds_write2_b32 v56, v36, v37 offset1:1
	ds_write2_b32 v52, v38, v39 offset1:1
	s_cbranch_vccnz .LBB0_278
	s_ashr_i32 s21, s20, 31
	v_lshl_add_u64 v[36:37], s[20:21], 0, v[72:73]
	v_lshl_add_u64 v[36:37], v[36:37], 2, s[18:19]
	v_mov_b32_e32 v38, v118
	s_nop 0
	v_mov_b32_e32 v36, v119
	s_waitcnt vmcnt(1)
	v_pk_mul_f32 v[40:41], v[30:31], v[38:39] op_sel_hi:[1,0]
	v_pk_mul_f32 v[42:43], v[28:29], v[38:39] op_sel_hi:[1,0]
	s_waitcnt vmcnt(0)
	v_pk_mul_f32 v[38:39], v[34:35], v[36:37] op_sel_hi:[1,0]
	v_pk_mul_f32 v[36:37], v[32:33], v[36:37] op_sel_hi:[1,0]
	s_cbranch_execnz .LBB0_189
	s_branch .LBB0_279

; __global__ void __launch_bounds__(NWAVES * 64, 2) hymba_fwd(Args args) {
;     ...
;             { int tid = threadIdx.x; asm volatile("" : "+v"(tid));
;               for (int t_ = bx; t_ < 256; t_ += G) { const int grow0 = MP + 32 * (t_ >> 4), gcol0 = 96 * (t_ & 15);
;                   SF_In f_{grow0, gcol0, SA, US, (OV_UG - OV_US) / 2}; small_gemm_tile<96, 8, 1, DM, 4>(lds, tid, HIN, DM, (const bf16*)(wl + WO_IN), grow0, gcol0, f_); } }
.LBB0_564:
	v_readlane_b32 s0, v253, 35
	v_readlane_b32 s1, v253, 36
	v_mov_b32_e32 v5, v0
	s_andn2_b64 vcc, exec, s[0:1]
	s_cbranch_vccnz .LBB0_576
	v_bfe_u32 v4, v5, 4, 2
	v_lshlrev_b32_e32 v2, 3, v4
	s_movk_i32 s0, 0x300
	v_and_b32_e32 v24, 15, v5
	v_lshl_add_u32 v4, v4, 4, 0
	v_cmp_gt_i32_e32 vcc, s0, v5
	v_lshlrev_b32_e32 v6, 1, v2
	s_cmpk_lt_i32 s56, 0x80
	s_cbranch_scc1 .LBB0_576
	s_add_i32 s4, s56, 0xffffff80
	s_add_i32 s5, s56, 0xffffff80
	s_branch .LBB0_567
.LBB0_566:
	s_or_b64 exec, exec, s[16:17]
	s_addk_i32 s5, 0x80
	s_addk_i32 s4, 0x80
	s_cmpk_gt_i32 s5, 0xff
	s_barrier
	s_cbranch_scc1 .LBB0_576
; #define LAS __attribute__((address_space(3)))
; #define SGT_LOAD(S_, KS_) do { _Pragma("unroll") for (int u = 0; u < U; ++u) { a0[S_][u] = *(const bf16x8*)(ap + (KS_) + 32 * u); if (MB == 2) a1[S_][u] = *(const bf16x8*)(ap + (size_t)16 * lda + (KS_) + 32 * u); \
;         _Pragma("unroll") for (int n = 0; n < NBW; ++n) b[S_][u][n] = *(const bf16x8*)(bp + (size_t)n * 16 * K + (KS_) + 32 * u); } } while (0)
; #define SGT_MMA(S_) do { _Pragma("unroll") for (int u = 0; u < U; ++u) _Pragma("unroll") for (int n = 0; n < NBW; ++n) { acc[0][n] = __builtin_amdgcn_mfma_f32_16x16x32_bf16(b[S_][u][n], a0[S_][u], acc[0][n], 0, 0, 0); \
;         if (MB == 2) acc[MB - 1][n] = __builtin_amdgcn_mfma_f32_16x16x32_bf16(b[S_][u][n], a1[S_][u], acc[MB - 1][n], 0, 0, 0); } } while (0)
;     static_assert(WK * WN == 8 && TN % (16 * WN) == 0 && (K / WK) % (32 * U) == 0, "wave split");
;     constexpr int NBW = TN / (16 * WN), P = TN + 4, KPER = K / WK;
;     const int lane = tid & 63, wave = __builtin_amdgcn_readfirstlane(tid >> 6), wk = wave / WN, wn = wave % WN, fr = lane & 15, fq = lane >> 4;
;     const int k0 = wk * KPER;
;     f32x4 acc[MB][NBW];
; #pragma unroll
;     for (int m = 0; m < MB; ++m)
; #pragma unroll
;         for (int n = 0; n < NBW; ++n) acc[m][n] = (f32x4){0.f, 0.f, 0.f, 0.f};
;     const bf16* ap = A + (size_t)(row0 + fr) * lda + k0 + 8 * fq;
;     const bf16* bp = Bt + (size_t)(col0 + wn * (TN / WN) + fr) * K + k0 + 8 * fq;
;     bf16x8 a0[2][U], a1[2][U], b[2][U][NBW];
;     ...
;     constexpr bool ONEPASS = 16 * MB * (TN / 4) <= NWAVES * 64;
;     typename F::Pre pre{};
;     if constexpr (ONEPASS) { if (tid < 16 * MB * (TN / 4)) pre = f.prefetch(tid / (TN / 4), 4 * (tid % (TN / 4))); }
;     SGT_LOAD(0, 0);
; #pragma unroll 1
;     for (int ks = 0; ks < KPER; ks += 64 * U) {
;         if (ks + 32 * U < KPER) SGT_LOAD(1, ks + 32 * U);
;         SGT_MMA(0);
;         if (ks + 64 * U < KPER) SGT_LOAD(0, ks + 64 * U);
;         if (ks + 32 * U < KPER) SGT_MMA(1);
;     }
;     ...
;     if constexpr (PREBAR) { asm volatile("s_waitcnt vmcnt(0)" ::: "memory"); __syncthreads(); }
;     LAS float* red = (LAS float*)lds;
; #pragma unroll
;     for (int m = 0; m < MB; ++m)
; #pragma unroll
;         for (int n = 0; n < NBW; ++n) *(LAS f32x4*)(red + (size_t)((wk * 16 * MB + 16 * m + fr) * P + wn * (TN / WN) + 16 * n + 4 * fq)) = acc[m][n];
;     __syncthreads();
.LBB0_567:
	s_lshl_b32 s0, s5, 1
	s_and_b32 s22, s0, 0xffffffe0
	s_and_b32 s0, s5, 15
	s_mul_i32 s17, s0, 0x60
	v_readfirstlane_b32 s0, v5
	s_addk_i32 s22, 0x4000
	s_ashr_i32 s16, s0, 6
	s_lshl_b32 s0, s16, 8
	v_or_b32_e32 v2, s17, v24
	v_lshlrev_b32_e32 v8, 11, v2
	v_add3_u32 v8, v8, s0, v6
	v_or_b32_e32 v2, s22, v24
	v_lshlrev_b32_e32 v9, 11, v2
	v_add3_u32 v9, v9, s0, v6
	s_mov_b64 s[68:69], s[8:9]
	s_add_u32 s70, s8, 0x8000
	s_addc_u32 s71, s9, 0
	s_add_u32 s72, s8, 0x10000
	s_addc_u32 s73, s9, 0
	s_add_u32 s74, s8, 0x18000
	s_addc_u32 s75, s9, 0
	s_add_u32 s76, s8, 0x20000
	s_addc_u32 s77, s9, 0
	s_add_u32 s78, s8, 0x28000
	s_addc_u32 s79, s9, 0
	s_mov_b64 s[80:81], s[10:11]
	s_add_u32 s82, s10, 0x8000
	s_addc_u32 s83, s11, 0
	global_load_dwordx4 v[28:31], v9, s[80:81]
	global_load_dwordx4 v[44:47], v9, s[82:83]
	global_load_dwordx4 v[10:13], v8, s[68:69]
	global_load_dwordx4 v[14:17], v8, s[70:71]
	global_load_dwordx4 v[18:21], v8, s[72:73]
	global_load_dwordx4 v[128:131], v8, s[74:75]
	global_load_dwordx4 v[132:135], v8, s[76:77]
	global_load_dwordx4 v[136:139], v8, s[78:79]
	global_load_dwordx4 v[32:35], v9, s[80:81] offset:64
	global_load_dwordx4 v[48:51], v9, s[82:83] offset:64
	global_load_dwordx4 v[140:143], v8, s[68:69] offset:64
	global_load_dwordx4 v[176:179], v8, s[70:71] offset:64
	global_load_dwordx4 v[182:185], v8, s[72:73] offset:64
	global_load_dwordx4 v[186:189], v8, s[74:75] offset:64
	global_load_dwordx4 v[190:193], v8, s[76:77] offset:64
	global_load_dwordx4 v[194:197], v8, s[78:79] offset:64
	global_load_dwordx4 v[36:39], v9, s[80:81] offset:128
	global_load_dwordx4 v[52:55], v9, s[82:83] offset:128
	global_load_dwordx4 v[198:201], v8, s[68:69] offset:128
	global_load_dwordx4 v[202:205], v8, s[70:71] offset:128
	global_load_dwordx4 v[206:209], v8, s[72:73] offset:128
	global_load_dwordx4 v[214:217], v8, s[74:75] offset:128
	global_load_dwordx4 v[218:221], v8, s[76:77] offset:128
	global_load_dwordx4 v[222:225], v8, s[78:79] offset:128
	global_load_dwordx4 v[40:43], v9, s[80:81] offset:192
	global_load_dwordx4 v[56:59], v9, s[82:83] offset:192
	global_load_dwordx4 v[226:229], v8, s[68:69] offset:192
	global_load_dwordx4 v[230:233], v8, s[70:71] offset:192
	global_load_dwordx4 v[234:237], v8, s[72:73] offset:192
	global_load_dwordx4 v[238:241], v8, s[74:75] offset:192
	global_load_dwordx4 v[242:245], v8, s[76:77] offset:192
	global_load_dwordx4 v[248:251], v8, s[78:79] offset:192
	v_lshl_or_b32 v2, s16, 5, v24
	s_movk_i32 s0, 0x190
	v_mad_u32_u24 v22, v2, s0, v4
	s_waitcnt vmcnt(24)
	v_mfma_f32_16x16x32_bf16 v[60:63], v[10:13], v[28:31], 0
	v_mfma_f32_16x16x32_bf16 v[84:87], v[10:13], v[44:47], 0
	v_mfma_f32_16x16x32_bf16 v[64:67], v[14:17], v[28:31], 0
	v_mfma_f32_16x16x32_bf16 v[108:111], v[14:17], v[44:47], 0
	v_mfma_f32_16x16x32_bf16 v[68:71], v[18:21], v[28:31], 0
	v_mfma_f32_16x16x32_bf16 v[112:115], v[18:21], v[44:47], 0
	v_mfma_f32_16x16x32_bf16 v[72:75], v[128:131], v[28:31], 0
	v_mfma_f32_16x16x32_bf16 v[116:119], v[128:131], v[44:47], 0
	v_mfma_f32_16x16x32_bf16 v[76:79], v[132:135], v[28:31], 0
	v_mfma_f32_16x16x32_bf16 v[120:123], v[132:135], v[44:47], 0
	v_mfma_f32_16x16x32_bf16 v[80:83], v[136:139], v[28:31], 0
	v_mfma_f32_16x16x32_bf16 v[124:127], v[136:139], v[44:47], 0
	s_waitcnt vmcnt(16)
	v_mfma_f32_16x16x32_bf16 v[60:63], v[140:143], v[32:35], v[60:63]
	v_mfma_f32_16x16x32_bf16 v[84:87], v[140:143], v[48:51], v[84:87]
	v_mfma_f32_16x16x32_bf16 v[64:67], v[176:179], v[32:35], v[64:67]
	v_mfma_f32_16x16x32_bf16 v[108:111], v[176:179], v[48:51], v[108:111]
	v_mfma_f32_16x16x32_bf16 v[68:71], v[182:185], v[32:35], v[68:71]
	v_mfma_f32_16x16x32_bf16 v[112:115], v[182:185], v[48:51], v[112:115]
	v_mfma_f32_16x16x32_bf16 v[72:75], v[186:189], v[32:35], v[72:75]
	v_mfma_f32_16x16x32_bf16 v[116:119], v[186:189], v[48:51], v[116:119]
	v_mfma_f32_16x16x32_bf16 v[76:79], v[190:193], v[32:35], v[76:79]
	v_mfma_f32_16x16x32_bf16 v[120:123], v[190:193], v[48:51], v[120:123]
	v_mfma_f32_16x16x32_bf16 v[80:83], v[194:197], v[32:35], v[80:83]
	v_mfma_f32_16x16x32_bf16 v[124:127], v[194:197], v[48:51], v[124:127]
	s_waitcnt vmcnt(8)
	v_mfma_f32_16x16x32_bf16 v[60:63], v[198:201], v[36:39], v[60:63]
	v_mfma_f32_16x16x32_bf16 v[84:87], v[198:201], v[52:55], v[84:87]
	v_mfma_f32_16x16x32_bf16 v[64:67], v[202:205], v[36:39], v[64:67]
	v_mfma_f32_16x16x32_bf16 v[108:111], v[202:205], v[52:55], v[108:111]
	v_mfma_f32_16x16x32_bf16 v[68:71], v[206:209], v[36:39], v[68:71]
	v_mfma_f32_16x16x32_bf16 v[112:115], v[206:209], v[52:55], v[112:115]
	v_mfma_f32_16x16x32_bf16 v[72:75], v[214:217], v[36:39], v[72:75]
	v_mfma_f32_16x16x32_bf16 v[116:119], v[214:217], v[52:55], v[116:119]
	v_mfma_f32_16x16x32_bf16 v[76:79], v[218:221], v[36:39], v[76:79]
	v_mfma_f32_16x16x32_bf16 v[120:123], v[218:221], v[52:55], v[120:123]
	v_mfma_f32_16x16x32_bf16 v[80:83], v[222:225], v[36:39], v[80:83]
	v_mfma_f32_16x16x32_bf16 v[124:127], v[222:225], v[52:55], v[124:127]
	s_waitcnt vmcnt(0)
	v_mfma_f32_16x16x32_bf16 v[60:63], v[226:229], v[40:43], v[60:63]
	v_mfma_f32_16x16x32_bf16 v[84:87], v[226:229], v[56:59], v[84:87]
	v_mfma_f32_16x16x32_bf16 v[64:67], v[230:233], v[40:43], v[64:67]
	v_mfma_f32_16x16x32_bf16 v[108:111], v[230:233], v[56:59], v[108:111]
	v_mfma_f32_16x16x32_bf16 v[68:71], v[234:237], v[40:43], v[68:71]
	v_mfma_f32_16x16x32_bf16 v[112:115], v[234:237], v[56:59], v[112:115]
	v_mfma_f32_16x16x32_bf16 v[72:75], v[238:241], v[40:43], v[72:75]
	v_mfma_f32_16x16x32_bf16 v[116:119], v[238:241], v[56:59], v[116:119]
	v_mfma_f32_16x16x32_bf16 v[76:79], v[242:245], v[40:43], v[76:79]
	v_mfma_f32_16x16x32_bf16 v[120:123], v[242:245], v[56:59], v[120:123]
	v_mfma_f32_16x16x32_bf16 v[80:83], v[248:251], v[40:43], v[80:83]
	v_mfma_f32_16x16x32_bf16 v[124:127], v[248:251], v[56:59], v[124:127]
	ds_write_b128 v22, v[60:63]
	ds_write_b128 v22, v[84:87] offset:6400
	ds_write_b128 v22, v[64:67] offset:64
	ds_write_b128 v22, v[108:111] offset:6464
	ds_write_b128 v22, v[68:71] offset:128
	ds_write_b128 v22, v[112:115] offset:6528
	ds_write_b128 v22, v[72:75] offset:192
	ds_write_b128 v22, v[116:119] offset:6592
	ds_write_b128 v22, v[76:79] offset:256
	ds_write_b128 v22, v[120:123] offset:6656
	ds_write_b128 v22, v[80:83] offset:320
	ds_write_b128 v22, v[124:127] offset:6720
	s_waitcnt lgkmcnt(0)
	s_barrier
	s_and_saveexec_b64 s[16:17], vcc
	s_cbranch_execz .LBB0_566
	s_and_b32 s23, s4, 15
	s_mulk_i32 s23, 0x60
	v_lshlrev_b32_e32 v7, 2, v5
	v_lshl_add_u32 v14, v5, 4, 0
	s_mov_b64 s[18:19], 0
	v_mov_b32_e32 v15, v5
	s_branch .LBB0_570

; #define LAS __attribute__((address_space(3)))
; __device__ __forceinline__ void p0_t_finish(const TItem& t, int lane, const f32x4 (&v)[8], LAS float* scr) {
; #pragma unroll
;     for (int i = 0; i < 8; ++i) { const int kk = 8 * i + (lane >> 3); f32x4 x = v[i]; if (t.gs) x = x * t.gs[t.k0 + kk]; LAS float* d = scr + kk * 33 + 4 * (lane & 7); d[0] = x[0]; d[1] = x[1]; d[2] = x[2]; d[3] = x[3]; }
.LBB0_811:
	s_cmp_lg_u64 s[18:19], 0
	s_cselect_b64 s[34:35], -1, 0
	s_cmp_eq_u64 s[18:19], 0
	s_cbranch_scc1 .LBB0_835
	s_ashr_i32 s31, s30, 31
	v_ashrrev_i32_e32 v69, 31, v68
	v_lshl_add_u64 v[70:71], s[30:31], 0, v[72:73]
	v_lshl_add_u64 v[68:69], v[68:69], 2, s[18:19]
	v_lshl_add_u64 v[70:71], v[70:71], 2, s[18:19]
	global_load_dword v68, v[68:69], off
	s_nop 0
	global_load_dword v108, v[70:71], off offset:64
	global_load_dword v109, v[70:71], off offset:96
	global_load_dword v110, v[70:71], off offset:128
	global_load_dword v111, v[70:71], off offset:160
	global_load_dword v112, v[70:71], off offset:192
	global_load_dword v113, v[70:71], off offset:224
	global_load_dword v90, v[70:71], off offset:32
	s_waitcnt vmcnt(0)
	v_pk_mul_f32 v[76:77], v[62:63], v[68:69] op_sel_hi:[1,0]
	v_pk_mul_f32 v[78:79], v[60:61], v[68:69] op_sel_hi:[1,0]
	s_waitcnt vmcnt(0)
	v_pk_mul_f32 v[70:71], v[66:67], v[90:91] op_sel_hi:[1,0]
	v_pk_mul_f32 v[68:69], v[64:65], v[90:91] op_sel_hi:[1,0]
	s_cbranch_execnz .LBB0_814

; #define LAS __attribute__((address_space(3)))
; __device__ __forceinline__ void p0_t_finish(const TItem& t, int lane, const f32x4 (&v)[8], LAS float* scr) {
; #pragma unroll
;     for (int i = 0; i < 8; ++i) { const int kk = 8 * i + (lane >> 3); f32x4 x = v[i]; if (t.gs) x = x * t.gs[t.k0 + kk]; LAS float* d = scr + kk * 33 + 4 * (lane & 7); d[0] = x[0]; d[1] = x[1]; d[2] = x[2]; d[3] = x[3]; }
.LBB0_814:
	ds_write2_b32 v88, v78, v79 offset1:1
	ds_write2_b32 v88, v76, v77 offset0:2 offset1:3
	v_add_u32_e32 v76, 0x420, v88
	s_waitcnt vmcnt(0)
	v_cndmask_b32_e64 v60, 0, 1, s[34:35]
	ds_write2_b32 v76, v68, v69 offset1:1
	v_add_u32_e32 v68, 0x428, v88
	v_cmp_ne_u32_e64 s[0:1], 1, v60
	s_andn2_b64 vcc, exec, s[34:35]
	ds_write2_b32 v68, v70, v71 offset1:1
	s_cbranch_vccnz .LBB0_836
	s_ashr_i32 s31, s30, 31
	v_lshl_add_u64 v[60:61], s[30:31], 0, v[72:73]
	v_lshl_add_u64 v[60:61], v[60:61], 2, s[18:19]
	v_mov_b32_e32 v62, v108
	s_nop 0
	v_mov_b32_e32 v60, v109
	s_waitcnt vmcnt(0)
	v_pk_mul_f32 v[64:65], v[54:55], v[62:63] op_sel_hi:[1,0]
	v_pk_mul_f32 v[66:67], v[52:53], v[62:63] op_sel_hi:[1,0]
	s_waitcnt vmcnt(0)
	v_pk_mul_f32 v[62:63], v[58:59], v[60:61] op_sel_hi:[1,0]
	v_pk_mul_f32 v[60:61], v[56:57], v[60:61] op_sel_hi:[1,0]
	s_cbranch_execnz .LBB0_817

; #define LAS __attribute__((address_space(3)))
; __device__ __forceinline__ void p0_t_finish(const TItem& t, int lane, const f32x4 (&v)[8], LAS float* scr) {
; #pragma unroll
;     for (int i = 0; i < 8; ++i) { const int kk = 8 * i + (lane >> 3); f32x4 x = v[i]; if (t.gs) x = x * t.gs[t.k0 + kk]; LAS float* d = scr + kk * 33 + 4 * (lane & 7); d[0] = x[0]; d[1] = x[1]; d[2] = x[2]; d[3] = x[3]; }
.LBB0_817:
	v_add_u32_e32 v69, 0x840, v88
	s_waitcnt vmcnt(0)
	ds_write2_b32 v69, v66, v67 offset1:1
	v_add_u32_e32 v66, 0x848, v88
	ds_write2_b32 v66, v64, v65 offset1:1
	v_add_u32_e32 v64, 0xc60, v88
	ds_write2_b32 v64, v60, v61 offset1:1
	v_add_u32_e32 v60, 0xc68, v88
	s_and_b64 vcc, exec, s[0:1]
	ds_write2_b32 v60, v62, v63 offset1:1
	s_cbranch_vccnz .LBB0_837
	s_ashr_i32 s31, s30, 31
	s_waitcnt vmcnt(0)
	v_lshl_add_u64 v[52:53], s[30:31], 0, v[72:73]
	v_lshl_add_u64 v[52:53], v[52:53], 2, s[18:19]
	v_mov_b32_e32 v54, v110
	s_nop 0
	v_mov_b32_e32 v52, v111
	s_waitcnt vmcnt(0)
	v_pk_mul_f32 v[56:57], v[46:47], v[54:55] op_sel_hi:[1,0]
	v_pk_mul_f32 v[58:59], v[44:45], v[54:55] op_sel_hi:[1,0]
	s_waitcnt vmcnt(0)
	v_pk_mul_f32 v[54:55], v[50:51], v[52:53] op_sel_hi:[1,0]
	v_pk_mul_f32 v[52:53], v[48:49], v[52:53] op_sel_hi:[1,0]
	s_cbranch_execnz .LBB0_820

; #define LAS __attribute__((address_space(3)))
; __device__ __forceinline__ void p0_t_finish(const TItem& t, int lane, const f32x4 (&v)[8], LAS float* scr) {
; #pragma unroll
;     for (int i = 0; i < 8; ++i) { const int kk = 8 * i + (lane >> 3); f32x4 x = v[i]; if (t.gs) x = x * t.gs[t.k0 + kk]; LAS float* d = scr + kk * 33 + 4 * (lane & 7); d[0] = x[0]; d[1] = x[1]; d[2] = x[2]; d[3] = x[3]; }
.LBB0_820:
	v_add_u32_e32 v61, 0x1080, v88
	s_waitcnt vmcnt(0)
	ds_write2_b32 v61, v58, v59 offset1:1
	v_add_u32_e32 v58, 0x1088, v88
	ds_write2_b32 v58, v56, v57 offset1:1
	v_add_u32_e32 v56, 0x14a0, v88
	ds_write2_b32 v56, v52, v53 offset1:1
	v_add_u32_e32 v52, 0x14a8, v88
	s_and_b64 vcc, exec, s[0:1]
	ds_write2_b32 v52, v54, v55 offset1:1
	s_cbranch_vccnz .LBB0_838
	s_ashr_i32 s31, s30, 31
	s_waitcnt vmcnt(0)
	v_lshl_add_u64 v[44:45], s[30:31], 0, v[72:73]
	v_lshl_add_u64 v[44:45], v[44:45], 2, s[18:19]
	v_mov_b32_e32 v46, v112
	s_nop 0
	v_mov_b32_e32 v44, v113
	s_waitcnt vmcnt(0)
	v_pk_mul_f32 v[48:49], v[38:39], v[46:47] op_sel_hi:[1,0]
	v_pk_mul_f32 v[50:51], v[36:37], v[46:47] op_sel_hi:[1,0]
	s_waitcnt vmcnt(0)
	v_pk_mul_f32 v[46:47], v[42:43], v[44:45] op_sel_hi:[1,0]
	v_pk_mul_f32 v[44:45], v[40:41], v[44:45] op_sel_hi:[1,0]
	s_cbranch_execnz .LBB0_823

; #define GAS __attribute__((address_space(1)))
; #define LAS __attribute__((address_space(3)))
; #define LDS_WAIT() asm volatile("s_waitcnt lgkmcnt(0)" ::: "memory")
; __device__ __forceinline__ unsigned pk2(float lo, float hi) { unsigned r; asm("v_cvt_pk_bf16_f32 %0, %1, %2" : "=v"(r) : "v"(lo), "v"(hi)); return r; }
; __device__ __forceinline__ void p0_t_finish(const TItem& t, int lane, const f32x4 (&v)[8], LAS float* scr) {
; #pragma unroll
;     for (int i = 0; i < 8; ++i) { const int kk = 8 * i + (lane >> 3); f32x4 x = v[i]; if (t.gs) x = x * t.gs[t.k0 + kk]; LAS float* d = scr + kk * 33 + 4 * (lane & 7); d[0] = x[0]; d[1] = x[1]; d[2] = x[2]; d[3] = x[3]; }
;     LDS_WAIT(); asm volatile("" ::: "memory");
;     const int c = lane & 7;
; #pragma unroll
;     for (int j = 0; j < 4; ++j) { const int n = (lane >> 3) + 8 * j; const LAS float* s = scr + (8 * c) * 33 + n;
;         v4u o; o.x = pk2(s[0 * 33], s[1 * 33]); o.y = pk2(s[2 * 33], s[3 * 33]); o.z = pk2(s[4 * 33], s[5 * 33]); o.w = pk2(s[6 * 33], s[7 * 33]);
;         *(GAS v4u*)(t.WT + (size_t)(t.n0 + n) * t.K + t.k0 + 8 * c) = o; }
.LBB0_823:
	v_add_u32_e32 v53, 0x18c0, v88
	s_waitcnt vmcnt(0)
	ds_write2_b32 v53, v50, v51 offset1:1
	v_add_u32_e32 v50, 0x18c8, v88
	ds_write2_b32 v50, v48, v49 offset1:1
	v_add_u32_e32 v48, 0x1ce0, v88
	ds_write2_b32 v48, v44, v45 offset1:1
	v_add_u32_e32 v44, 0x1ce8, v88
	ds_write2_b32 v44, v46, v47 offset1:1
	s_waitcnt lgkmcnt(0)
	s_waitcnt vmcnt(0)
	ds_read2_b32 v[40:41], v87 offset0:33 offset1:41
	ds_read2_b32 v[42:43], v87 offset1:8
	ds_read2_b32 v[46:47], v87 offset0:66 offset1:74
	ds_read2_b32 v[54:55], v87 offset0:99 offset1:107
	s_waitcnt lgkmcnt(2)
	v_cvt_pk_bf16_f32 v36, v42, v40
	ds_read2_b32 v[62:63], v87 offset0:132 offset1:140
	ds_read2_b32 v[70:71], v87 offset0:165 offset1:173
	ds_read2_b32 v[78:79], v87 offset0:198 offset1:206
	ds_read2_b32 v[90:91], v87 offset0:231 offset1:239
	v_or_b32_e32 v40, s28, v72
	v_mul_hi_i32_i24_e32 v93, s14, v40
	v_mul_i32_i24_e32 v92, s14, v40
	v_lshl_add_u64 v[92:93], v[92:93], 1, s[12:13]
	s_lshl_b64 s[0:1], s[30:31], 1
	v_lshl_add_u64 v[92:93], v[92:93], 0, s[0:1]
	v_mov_b32_e32 v75, v3
	v_lshl_add_u64 v[92:93], v[92:93], 0, v[74:75]
	v_or_b32_e32 v40, s28, v80
	s_waitcnt lgkmcnt(4)
	v_cvt_pk_bf16_f32 v37, v46, v54
	s_waitcnt lgkmcnt(2)
	v_cvt_pk_bf16_f32 v38, v62, v70
	s_waitcnt lgkmcnt(0)
	v_cvt_pk_bf16_f32 v39, v78, v90
	global_store_dwordx4 v[92:93], v[36:39], off
	s_andn2_b64 vcc, exec, s[20:21]
	s_nop 0
	v_cvt_pk_bf16_f32 v36, v43, v41
	v_mul_hi_i32_i24_e32 v41, s14, v40
	v_mul_i32_i24_e32 v40, s14, v40
	v_lshl_add_u64 v[40:41], v[40:41], 1, s[12:13]
	v_lshl_add_u64 v[40:41], v[40:41], 0, s[0:1]
	v_lshl_add_u64 v[40:41], v[40:41], 0, v[74:75]
	v_cvt_pk_bf16_f32 v37, v47, v55
	v_cvt_pk_bf16_f32 v38, v63, v71
	v_cvt_pk_bf16_f32 v39, v79, v91
	global_store_dwordx4 v[40:41], v[36:39], off
	ds_read2_b32 v[40:41], v87 offset0:16 offset1:24
	ds_read2_b32 v[42:43], v87 offset0:49 offset1:57
	s_waitcnt lgkmcnt(0)
	v_cvt_pk_bf16_f32 v36, v40, v42
	ds_read2_b32 v[46:47], v87 offset0:82 offset1:90
	ds_read2_b32 v[54:55], v87 offset0:115 offset1:123
	ds_read2_b32 v[62:63], v87 offset0:148 offset1:156
	ds_read2_b32 v[70:71], v87 offset0:181 offset1:189
	ds_read2_b32 v[78:79], v87 offset0:214 offset1:222
	ds_read2_b32 v[90:91], v87 offset0:247 offset1:255
	v_or_b32_e32 v40, s28, v81
	v_mul_hi_i32_i24_e32 v93, s14, v40
	v_mul_i32_i24_e32 v92, s14, v40
	v_lshl_add_u64 v[92:93], v[92:93], 1, s[12:13]
	v_lshl_add_u64 v[92:93], v[92:93], 0, s[0:1]
	v_lshl_add_u64 v[92:93], v[92:93], 0, v[74:75]
	v_or_b32_e32 v40, s28, v82
	s_waitcnt lgkmcnt(4)
	v_cvt_pk_bf16_f32 v37, v46, v54
	s_waitcnt lgkmcnt(2)
	v_cvt_pk_bf16_f32 v38, v62, v70
	s_waitcnt lgkmcnt(0)
	v_cvt_pk_bf16_f32 v39, v78, v90
	global_store_dwordx4 v[92:93], v[36:39], off
	s_nop 1
	v_cvt_pk_bf16_f32 v36, v41, v43
	v_mul_hi_i32_i24_e32 v41, s14, v40
	v_mul_i32_i24_e32 v40, s14, v40
	v_lshl_add_u64 v[40:41], v[40:41], 1, s[12:13]
	v_lshl_add_u64 v[40:41], v[40:41], 0, s[0:1]
	v_lshl_add_u64 v[40:41], v[40:41], 0, v[74:75]
	v_cvt_pk_bf16_f32 v37, v47, v55
	v_cvt_pk_bf16_f32 v38, v63, v71
	v_cvt_pk_bf16_f32 v39, v79, v91
	global_store_dwordx4 v[40:41], v[36:39], off
	s_waitcnt lgkmcnt(0)
	s_cbranch_vccnz .LBB0_754
	s_cmp_lg_u64 s[6:7], 0
	s_cselect_b64 s[12:13], -1, 0
	s_cmp_eq_u64 s[6:7], 0
	s_cbranch_scc1 .LBB0_839
	v_add_u32_e32 v36, s8, v72
	v_ashrrev_i32_e32 v37, 31, v36
	v_lshl_add_u64 v[36:37], v[36:37], 2, s[6:7]
	global_load_dword v38, v[36:37], off
	s_nop 0
	global_load_dword v114, v[36:37], off offset:64
	global_load_dword v115, v[36:37], off offset:96
	global_load_dword v116, v[36:37], off offset:128
	global_load_dword v117, v[36:37], off offset:160
	global_load_dword v118, v[36:37], off offset:192
	global_load_dword v119, v[36:37], off offset:224
	global_load_dword v36, v[36:37], off offset:32
	s_waitcnt vmcnt(1)
	v_pk_mul_f32 v[40:41], v[6:7], v[38:39] op_sel_hi:[1,0]
	v_pk_mul_f32 v[42:43], v[4:5], v[38:39] op_sel_hi:[1,0]
	s_waitcnt vmcnt(0)
	v_pk_mul_f32 v[38:39], v[10:11], v[36:37] op_sel_hi:[1,0]
	v_pk_mul_f32 v[36:37], v[8:9], v[36:37] op_sel_hi:[1,0]
	s_cbranch_execnz .LBB0_827

; #define LAS __attribute__((address_space(3)))
; __device__ __forceinline__ void p0_t_finish(const TItem& t, int lane, const f32x4 (&v)[8], LAS float* scr) {
; #pragma unroll
;     for (int i = 0; i < 8; ++i) { const int kk = 8 * i + (lane >> 3); f32x4 x = v[i]; if (t.gs) x = x * t.gs[t.k0 + kk]; LAS float* d = scr + kk * 33 + 4 * (lane & 7); d[0] = x[0]; d[1] = x[1]; d[2] = x[2]; d[3] = x[3]; }
.LBB0_827:
	ds_write2_b32 v88, v42, v43 offset1:1
	ds_write2_b32 v88, v40, v41 offset0:2 offset1:3
	ds_write2_b32 v76, v36, v37 offset1:1
	v_cndmask_b32_e64 v36, 0, 1, s[12:13]
	v_cmp_ne_u32_e64 s[0:1], 1, v36
	s_andn2_b64 vcc, exec, s[12:13]
	ds_write2_b32 v68, v38, v39 offset1:1
	s_cbranch_vccnz .LBB0_840
	s_ashr_i32 s9, s8, 31
	v_lshl_add_u64 v[36:37], s[8:9], 0, v[72:73]
	v_lshl_add_u64 v[36:37], v[36:37], 2, s[6:7]
	v_mov_b32_e32 v38, v114
	s_nop 0
	v_mov_b32_e32 v36, v115
	s_waitcnt vmcnt(1)
	v_pk_mul_f32 v[40:41], v[14:15], v[38:39] op_sel_hi:[1,0]
	v_pk_mul_f32 v[42:43], v[12:13], v[38:39] op_sel_hi:[1,0]
	s_waitcnt vmcnt(0)
	v_pk_mul_f32 v[38:39], v[18:19], v[36:37] op_sel_hi:[1,0]
	v_pk_mul_f32 v[36:37], v[16:17], v[36:37] op_sel_hi:[1,0]
	s_cbranch_execnz .LBB0_830

; #define LAS __attribute__((address_space(3)))
; __device__ __forceinline__ void p0_t_finish(const TItem& t, int lane, const f32x4 (&v)[8], LAS float* scr) {
; #pragma unroll
;     for (int i = 0; i < 8; ++i) { const int kk = 8 * i + (lane >> 3); f32x4 x = v[i]; if (t.gs) x = x * t.gs[t.k0 + kk]; LAS float* d = scr + kk * 33 + 4 * (lane & 7); d[0] = x[0]; d[1] = x[1]; d[2] = x[2]; d[3] = x[3]; }
.LBB0_830:
	s_and_b64 vcc, exec, s[0:1]
	ds_write2_b32 v69, v42, v43 offset1:1
	ds_write2_b32 v66, v40, v41 offset1:1
	ds_write2_b32 v64, v36, v37 offset1:1
	ds_write2_b32 v60, v38, v39 offset1:1
	s_cbranch_vccnz .LBB0_841
	s_ashr_i32 s9, s8, 31
	v_lshl_add_u64 v[36:37], s[8:9], 0, v[72:73]
	v_lshl_add_u64 v[36:37], v[36:37], 2, s[6:7]
	v_mov_b32_e32 v38, v116
	s_nop 0
	v_mov_b32_e32 v36, v117
	s_waitcnt vmcnt(1)
	v_pk_mul_f32 v[40:41], v[22:23], v[38:39] op_sel_hi:[1,0]
	v_pk_mul_f32 v[42:43], v[20:21], v[38:39] op_sel_hi:[1,0]
	s_waitcnt vmcnt(0)
	v_pk_mul_f32 v[38:39], v[26:27], v[36:37] op_sel_hi:[1,0]
	v_pk_mul_f32 v[36:37], v[24:25], v[36:37] op_sel_hi:[1,0]
	s_cbranch_execnz .LBB0_833

; #define LAS __attribute__((address_space(3)))
; __device__ __forceinline__ void p0_t_finish(const TItem& t, int lane, const f32x4 (&v)[8], LAS float* scr) {
; #pragma unroll
;     for (int i = 0; i < 8; ++i) { const int kk = 8 * i + (lane >> 3); f32x4 x = v[i]; if (t.gs) x = x * t.gs[t.k0 + kk]; LAS float* d = scr + kk * 33 + 4 * (lane & 7); d[0] = x[0]; d[1] = x[1]; d[2] = x[2]; d[3] = x[3]; }
.LBB0_833:
	s_and_b64 vcc, exec, s[0:1]
	ds_write2_b32 v61, v42, v43 offset1:1
	ds_write2_b32 v58, v40, v41 offset1:1
	ds_write2_b32 v56, v36, v37 offset1:1
	ds_write2_b32 v52, v38, v39 offset1:1
	s_cbranch_vccnz .LBB0_842
	s_ashr_i32 s9, s8, 31
	v_lshl_add_u64 v[36:37], s[8:9], 0, v[72:73]
	v_lshl_add_u64 v[36:37], v[36:37], 2, s[6:7]
	v_mov_b32_e32 v38, v118
	s_nop 0
	v_mov_b32_e32 v36, v119
	s_waitcnt vmcnt(1)
	v_pk_mul_f32 v[40:41], v[30:31], v[38:39] op_sel_hi:[1,0]
	v_pk_mul_f32 v[42:43], v[28:29], v[38:39] op_sel_hi:[1,0]
	s_waitcnt vmcnt(0)
	v_pk_mul_f32 v[38:39], v[34:35], v[36:37] op_sel_hi:[1,0]
	v_pk_mul_f32 v[36:37], v[32:33], v[36:37] op_sel_hi:[1,0]
	s_cbranch_execnz .LBB0_753
	s_branch .LBB0_843

;     __device__ __forceinline__ void init_rev(int M, int N, int G_, int c_) { init(M, N, G_, c_); nr = (c < nwg) ? (nwg - c + G - 1) / G : 0; rot = (c >> 3) & 3; if (rot >= nr) rot = 0; }
;     __device__ __forceinline__ bool next(int i, Unit& u) const { if (c >= nM || i >= 2) return false; u.pm = c; u.pn = i; u.ui = i; return true; }
; #define LAS __attribute__((address_space(3)))
; __device__ __forceinline__ int opq(int x) { asm volatile("" : "+s"(x)); return x; }
;     __device__ __forceinline__ bool next(int i, Unit& u) const { if (i >= nr) return false; int j = nr - 1 - i + rot; if (j >= nr) j -= nr; const bool ok = StaticOrder::next(j, u); u.ui = i; return ok; }
; __global__ void __launch_bounds__(NWAVES * 64, 2) hymba_fwd(Args args) {
;     ...
;                     pg8::Gemm g{HB, (const bf16*)(wl + WO_UP), MP, FF, opq(DM), 0, 0, (bx & 7) * 2, HB + (size_t)MP * DM, DM}; pg8::RevOrder S; S.init_rev(MP, FF, G, bx);
;                     pg8::EpiAct<1> E{HID, 256, 0, FF / 256, SB, nullptr, nullptr, nullptr, (const LAS float*)(lds + RT_OFF), HID + (size_t)MP * FF, FF, MP};
;                     { int t_ = threadIdx.x; asm volatile("" : "+v"(t_)); pg8::Unit u0_; if (S.next(0, u0_) && t_ < 256) E.pre = pg8::rtpre_load(SB, u0_.pm * 256 + t_); }
;                     pg8::gemm_phase<pg8::EpiAct<1>, pg8::RevOrder, PG8_ALIGN, PG8_SP2, true, true>(lds, g, S, E);
.LBB0_1329:
	s_andn2_b64 vcc, exec, s[0:1]
	s_cbranch_vccnz .LBB0_1618
	v_readlane_b32 s4, v252, 4
	v_readlane_b32 s5, v252, 5
	v_readlane_b32 s6, v252, 6
	v_readlane_b32 s7, v252, 7
	v_readlane_b32 s67, v252, 3
	v_readlane_b32 s68, v252, 0
	s_mov_b64 s[0:1], s[6:7]
	s_mov_b64 s[2:3], s[4:5]
	s_mov_b32 s92, 0
	s_add_u32 s4, s0, 0x3100000
	v_writelane_b32 v253, s4, 41
	s_addc_u32 s4, s1, 0
	v_writelane_b32 v253, s4, 33
	s_add_u32 s4, s0, 0x5200000
	s_addc_u32 s5, s1, 0
	s_add_u32 s71, s0, 0x7a00000
	v_writelane_b32 v254, s4, 46
	s_addc_u32 s72, s1, 0
	s_nop 0
	v_writelane_b32 v254, s5, 47
	s_add_u32 s4, s2, 0x2400000
	v_writelane_b32 v254, s4, 48
	s_addc_u32 s4, s3, 0
	v_writelane_b32 v254, s4, 50
	v_readlane_b32 s4, v253, 28
	s_add_u32 s6, s0, s4
	v_readlane_b32 s4, v253, 17
	s_addc_u32 s7, s1, 0
	v_readlane_b32 s5, v253, 18
	s_and_b64 s[4:5], s[4:5], exec
	s_mov_b32 s4, 0x7300000
	s_cselect_b32 s4, 0x7410000, s4
	s_add_u32 s10, s0, s4
	s_addc_u32 s11, s1, 0
	s_bitcmp0_b32 s68, 3
	s_cselect_b64 s[4:5], -1, 0
	v_writelane_b32 v254, s4, 56
	s_nop 1
	v_writelane_b32 v254, s5, 57
	s_add_u32 s4, s6, 0x1880000
	v_writelane_b32 v253, s4, 39
	s_addc_u32 s4, s7, 0
	s_add_u32 s8, s2, 0x2c00000
	s_addc_u32 s9, s3, 0
	s_add_u32 s2, s0, 0x7200000
	v_writelane_b32 v254, s4, 52
	s_addc_u32 s3, s1, 0
	v_writelane_b32 v254, s2, 54
	s_cmpk_lt_i32 s68, 0x100
	s_nop 0
	v_writelane_b32 v254, s3, 55
	s_cselect_b64 s[2:3], -1, 0
	v_writelane_b32 v253, s2, 51
	s_ashr_i32 s79, s68, 31
	s_ashr_i32 s5, s67, 31
	v_writelane_b32 v253, s3, 52
	s_lshr_b32 s2, s79, 29
	s_add_i32 s2, s68, s2
	s_ashr_i32 s3, s2, 3
	s_and_b32 s2, s2, -8
	s_sub_i32 s2, s68, s2
	s_lshl_b32 s4, s2, 5
	v_writelane_b32 v253, s5, 37
	s_add_u32 s5, s6, 0x680000
	v_writelane_b32 v254, s5, 23
	s_addc_u32 s5, s7, 0
	v_writelane_b32 v253, s5, 43
	s_lshl_b32 s5, s68, 1
	s_and_b32 s83, s5, 14
	s_add_u32 s37, s0, 0x5100000
	s_addc_u32 s38, s1, 0
	s_cmpk_lt_i32 s68, 0x400
	s_cselect_b64 s[6:7], -1, 0
	v_writelane_b32 v253, s6, 45
	s_mov_b32 s5, 0
	s_nop 0
	v_writelane_b32 v253, s7, 46
	s_sub_i32 s6, s67, s68
	s_add_i32 s7, s6, 0x3ff
	s_add_u32 s0, s0, 0xfa00000
	s_addc_u32 s1, s1, 0
	v_writelane_b32 v254, s0, 19
	s_cmp_lt_i32 s2, 0
	s_mul_i32 s2, s2, 33
	v_writelane_b32 v254, s1, 20
	s_cselect_b32 s0, s2, s4
	s_add_i32 s0, s0, s3
	s_ashr_i32 s1, s0, 31
	s_lshr_b32 s1, s1, 27
	s_add_i32 s1, s0, s1
	s_ashr_i32 s2, s1, 5
	s_and_b32 s1, s1, 0xffe0
	s_sub_i32 s1, s0, s1
	s_bfe_i32 s0, s1, 0x80000
	s_bfe_u32 s0, s0, 0x3000c
	s_add_i32 s3, s1, s0
	s_bfe_i32 s0, s3, 0x80000
	s_and_b32 s3, s3, 0xf8
	s_sub_i32 s1, s1, s3
	s_lshl_b32 s2, s2, 3
	s_sext_i32_i16 s4, s0
	s_sext_i32_i8 s1, s1
	s_lshr_b32 s0, s4, 3
	s_add_i32 s1, s2, s1
	s_ashr_i32 s12, s4, 3
	s_bitcmp1_b32 s1, 0
	v_writelane_b32 v253, s5, 49
	s_cselect_b64 s[2:3], -1, 0
	s_ashr_i32 s4, s1, 1
	s_ashr_i32 s5, s4, 31
	v_writelane_b32 v253, s1, 55
	s_ashr_i32 s1, s1, 31
	s_lshl_b64 s[4:5], s[4:5], 13
	v_writelane_b32 v254, s1, 28
	s_bfe_i64 s[0:1], s[0:1], 0x100000
	v_writelane_b32 v254, s0, 44
	s_cmp_lt_i32 s12, 2
	v_writelane_b32 v253, s8, 31
	v_writelane_b32 v254, s1, 45
	s_cselect_b64 s[0:1], -1, 0
	s_add_u32 s4, s8, s4
	v_writelane_b32 v253, s9, 35
	s_addc_u32 s5, s9, s5
	v_writelane_b32 v253, s4, 57
	v_writelane_b32 v254, s12, 26
	s_xor_b64 s[0:1], s[0:1], s[2:3]
	v_writelane_b32 v253, s5, 58
	s_abs_i32 s4, s67
	v_cvt_f32_u32_e32 v2, s4
	s_sub_i32 s2, 0, s4
	v_writelane_b32 v254, s0, 30
	v_rcp_iflag_f32_e32 v2, v2
	s_nop 0
	v_writelane_b32 v254, s1, 31
	s_sub_i32 s1, 0xfffffc01, s6
	s_max_i32 s1, s7, s1
	v_mul_f32_e32 v2, 0x4f7ffffe, v2
	v_cvt_u32_f32_e32 v2, v2
	s_xor_b32 s0, s7, s67
	s_ashr_i32 s0, s0, 31
	v_readfirstlane_b32 s3, v2
	s_mul_i32 s2, s2, s3
	s_mul_hi_u32 s2, s3, s2
	s_add_i32 s3, s3, s2
	s_mul_hi_u32 s2, s1, s3
	s_mul_i32 s3, s2, s4
	s_sub_i32 s1, s1, s3
	s_add_i32 s3, s2, 1
	s_sub_i32 s5, s1, s4
	s_cmp_ge_u32 s1, s4
	s_cselect_b32 s2, s3, s2
	s_cselect_b32 s1, s5, s1
	s_add_i32 s3, s2, 1
	s_cmp_ge_u32 s1, s4
	s_cselect_b32 s1, s3, s2
	s_xor_b32 s1, s1, s0
	s_sub_i32 s0, s1, s0
	v_writelane_b32 v253, s0, 59
	s_branch .LBB0_1333
